# stats-skip block now initialises its own lane-bound register (v67) instead of relying on a leftover value; otherwise identical to the previous version
# baseline (speedup 1.0000x reference)
.Lst_skip_wo:
	v_and_b32_e32 v67, 64, v237
	s_waitcnt vmcnt(0)
	v_pk_add_f32 v[60:61], v[60:61], v[62:63]
	v_xor_b32_e32 v64, 1, v237
	v_add_u32_e32 v67, 64, v67
	v_pk_add_f32 v[60:61], v[60:61], 0 op_sel_hi:[1,0]
	v_pk_add_f32 v[56:57], v[56:57], v[58:59]
	v_cmp_lt_i32_e32 vcc, v64, v67
	v_pk_add_f32 v[56:57], v[60:61], v[56:57]
	v_pk_add_f32 v[52:53], v[52:53], v[54:55]
	v_cndmask_b32_e32 v64, v237, v64, vcc
	v_pk_add_f32 v[52:53], v[56:57], v[52:53]
	v_pk_add_f32 v[48:49], v[48:49], v[50:51]
	v_lshlrev_b32_e32 v64, 2, v64
	v_pk_add_f32 v[48:49], v[52:53], v[48:49]
	ds_bpermute_b32 v50, v64, v48
	ds_bpermute_b32 v51, v64, v49
	v_cmp_eq_u32_e32 vcc, 0, v66
	v_lshl_add_u32 v52, v65, 3, s90
	s_and_saveexec_b64 s[10:11], vcc
	s_cbranch_execz .Lst_g1e_wo
	s_waitcnt lgkmcnt(0)
	v_pk_add_f32 v[48:49], v[48:49], v[50:51]
	s_nop 0
	v_pk_mul_f32 v[48:49], v[48:49], s[6:7] op_sel_hi:[1,0]
	s_nop 0
	v_fma_f32 v49, -v48, v48, v49
	v_max_f32_e32 v49, 0, v49
	v_add_f32_e32 v49, 0x3727c5ac, v49
	v_mul_f32_e32 v50, 0x4b800000, v49
	v_cmp_gt_f32_e64 s[24:25], s14, v49
	s_nop 1
	v_cndmask_b32_e64 v49, v49, v50, s[24:25]
	v_rsq_f32_e32 v49, v49
	s_nop 0
	v_mul_f32_e32 v50, 0x45800000, v49
	v_cndmask_b32_e64 v49, v49, v50, s[24:25]
	ds_write_b64 v52, v[48:49]
